# EpiResid epilogue rewrite (16B accesses via permlane16 swaps) + LUT copy loops unrolled in mixer A2/C; nothing else
# speedup vs baseline: 1.0022x; 1.0022x over previous
; template <bool EDGE>
; __device__ __forceinline__ void tile_load(TileLd& L, const bf16_t* kp, const bf16_t* vp, int S, int pos0, int dil, int k0, int lane) {
;     ...
;     for (int st = 0; st < 2; ++st) { int pos = pos0 + dil * (k0 + 16 * st + i16); if (EDGE) pos = min(max(pos, 0), S - 1);
;         const bf16_t* p = kp + (long)pos * NIN + quad * 8; L.k[st][0] = *(const bf16x8*)p; L.k[st][1] = *(const bf16x8*)(p + 32); }
; #pragma unroll
;     for (int i = 0; i < 4; ++i) { int pos = pos0 + dil * (k0 + 8 * i + (lane >> 3)); if (EDGE) pos = min(max(pos, 0), S - 1);
;         L.v[i] = *(const u32x4*)(vp + (long)pos * NIN + (lane & 7) * 8); }
; __device__ __forceinline__ void mixer_a2(Frame& F, const Trunk& T) {
;     ...
;         for (int i = lane; i < 387; i += 64) lut[i] = lutA[h * 387 + i];
;         asm volatile("s_waitcnt lgkmcnt(0)" ::: "memory");
;         {
;             const int pos0 = P0 + 32 * F.wave;
;             bf16x8 q[2][2]; f32x4 o[2][4]; float m[2], l[2];
; #pragma unroll
;             for (int g = 0; g < 2; ++g) { const bf16_t* qp = proj + (rowb + pos0 + 16 * g + i16) * NIN + C_QA + h * 64 + quad * 8; q[g][0] = *(const bf16x8*)qp; q[g][1] = *(const bf16x8*)(qp + 32);
;                 o[g][0] = z4; o[g][1] = z4; o[g][2] = z4; o[g][3] = z4; m[g] = -1e20f; l[g] = 0.f; }
;             if (pos0 >= 64 && pos0 + 96 <= T.S) a2_pass1<false>(kp, vp, T.S, pos0, lut, vimg, lane, q, o, m, l);
.LBB0_476:
	v_ashrrev_i32_e32 v185, 31, v184
	v_lshl_add_u64 v[0:1], v[184:185], 2, s[14:15]
	s_mov_b64 s[0:1], 0
	v_or_b32_e32 v2, 0xffffffc0, v198
	v_mov_b32_e32 v3, v241
	global_load_dword v8, v[0:1], off
	global_load_dword v9, v[0:1], off offset:256
	global_load_dword v10, v[0:1], off offset:512
	global_load_dword v11, v[0:1], off offset:768
	global_load_dword v12, v[0:1], off offset:1024
	global_load_dword v13, v[0:1], off offset:1280
	v_cmp_gt_u32_e32 vcc, 3, v198
	s_and_saveexec_b64 s[0:1], vcc
	global_load_dword v14, v[0:1], off offset:1536
	s_waitcnt vmcnt(0)
	ds_write_b32 v3, v14 offset:1536
	s_mov_b64 exec, s[0:1]
	ds_write_b32 v3, v8
	ds_write_b32 v3, v9 offset:256
	ds_write_b32 v3, v10 offset:512
	ds_write_b32 v3, v11 offset:768
	ds_write_b32 v3, v12 offset:1024
	ds_write_b32 v3, v13 offset:1280
	s_lshl_b32 s0, s9, 1
	s_add_i32 s0, s0, s38
	s_lshl_b32 s16, s0, 6
	s_ashr_i32 s17, s16, 31
	s_lshl_b64 s[0:1], s[16:17], 1
	v_lshl_add_u64 v[112:113], v[170:171], 0, s[0:1]
	v_lshl_add_u64 v[0:1], v[112:113], 0, v[174:175]
	v_add_co_u32_e32 v4, vcc, 0x28000, v0
	s_waitcnt lgkmcnt(0)
	global_load_dwordx4 v[8:11], v[0:1], off
	global_load_dwordx4 v[12:15], v[0:1], off offset:64
	v_addc_co_u32_e32 v5, vcc, 0, v1, vcc
	global_load_dwordx4 v[0:3], v[4:5], off
	s_nop 0
	global_load_dwordx4 v[4:7], v[4:5], off offset:64
	s_add_u32 s92, s39, s0
	s_addc_u32 s93, s40, s1
	v_lshl_add_u64 v[186:187], s[92:93], 0, v[156:157]
	s_mov_b64 s[0:1], -1
	s_and_b64 vcc, exec, s[10:11]
	s_cbranch_vccz .LBB0_500
	s_mov_b32 s0, s8
	s_movk_i32 s1, 0xffc0
	s_add_i32 s7, s0, s1
	v_add_u32_e32 v18, s7, v199
	v_mad_i64_i32 v[16:17], s[0:1], v18, s97, v[186:187]
	v_lshlrev_b32_e32 v32, 1, v201
	v_mov_b32_e32 v33, v157
	global_load_dwordx4 v[28:31], v[16:17], off offset:1536
	global_load_dwordx4 v[24:27], v[16:17], off offset:1600
	v_add_u32_e32 v16, 16, v18
	v_lshl_add_u64 v[118:119], s[92:93], 0, v[32:33]
	v_add_u32_e32 v36, s7, v200
	v_mad_i64_i32 v[16:17], s[0:1], v16, s97, v[186:187]
	v_mad_i64_i32 v[32:33], s[0:1], v36, s97, v[118:119]
	v_add_u32_e32 v34, 8, v36
	global_load_dwordx4 v[20:23], v[16:17], off offset:1536
	s_nop 0
	global_load_dwordx4 v[16:19], v[16:17], off offset:1600
	v_mad_i64_i32 v[34:35], s[0:1], v34, s97, v[118:119]
	global_load_dwordx4 v[80:83], v[32:33], off offset:3072
	global_load_dwordx4 v[84:87], v[34:35], off offset:3072
	v_add_u32_e32 v32, 16, v36
	v_mad_i64_i32 v[32:33], s[0:1], v32, s97, v[118:119]
	v_add_u32_e32 v34, 24, v36
	v_mad_i64_i32 v[34:35], s[0:1], v34, s97, v[118:119]
	global_load_dwordx4 v[88:91], v[32:33], off offset:3072
	global_load_dwordx4 v[92:95], v[34:35], off offset:3072
	v_mov_b32_e32 v34, v157
	v_mov_b32_e32 v35, v157
	v_mov_b32_e32 v161, v160
	v_mov_b32_e32 v32, v157
	v_mov_b32_e32 v33, v157
	v_mov_b64_e32 v[38:39], v[34:35]
	v_mov_b64_e32 v[42:43], v[34:35]
	v_mov_b64_e32 v[46:47], v[34:35]
	v_mov_b64_e32 v[66:67], v[34:35]
	v_mov_b64_e32 v[70:71], v[34:35]
	v_mov_b64_e32 v[74:75], v[34:35]
	v_mov_b64_e32 v[78:79], v[34:35]
	v_mov_b32_e32 v114, v157
	v_mov_b32_e32 v115, v157
	s_mov_b32 s7, 0
	s_mov_b64 s[24:25], -1
	v_mov_b64_e32 v[36:37], v[32:33]
	v_mov_b64_e32 v[40:41], v[32:33]
	v_mov_b64_e32 v[44:45], v[32:33]
	v_mov_b64_e32 v[64:65], v[32:33]
	v_mov_b64_e32 v[68:69], v[32:33]
	v_mov_b64_e32 v[72:73], v[32:33]
	v_mov_b64_e32 v[76:77], v[32:33]
	v_mov_b64_e32 v[116:117], v[160:161]
	s_branch .LBB0_482

; template <bool EDGE>
; __device__ __forceinline__ void mixer_c_item(const bf16_t* kp, const bf16_t* vp, int S, int P0, const LAS float* lut, LAS unsigned char* vimg, int lane,
;                                              const bf16x8 (&q)[3][2], f32x4 (&o)[3][4], float (&m)[3], float (&l)[3]) {
;     ...
;     const int klo_1 = max(i16 - 128, -P0), kspan_1 = min(i16 + 128, S - 1 - P0) - klo_1; const int klo_c[3] = {klo_1, klo_1, klo_1}, kspan_c[3] = {kspan_1, kspan_1, kspan_1}, ua_c[3] = {i16, i16, i16};
;     TileLd ta, tb; tile_load<EDGE>(ta, kp, vp, S, P0, 1, -128, lane);
; __device__ __forceinline__ void mixer_c(Frame& F, const Trunk& T, int layer) {
;     ...
;         int kvh, rest;
;         if (xmap) { kvh = j; rest = (F.bx & 7) * 256 + (F.bx >> 3) * NWAVES + F.wave; }
;         else { const int it = F.gw * per + j; if (it >= NIT) break; kvh = it / (MT / 16); rest = it % (MT / 16); }
;         const int b = rest / bps, P0 = (rest % bps) * 16;
;         const size_t rowb = (size_t)b * T.S; const int posq = P0 + i16;
;         const bf16_t* kp = proj + rowb * NIN + C_KC + kvh * 64; const bf16_t* vp = proj + rowb * NIN + C_VC + kvh * 64;
;         for (int i = lane; i < 771; i += 64) lut[i] = lutC[kvh * 771 + i];
;         asm volatile("s_waitcnt lgkmcnt(0)" ::: "memory");
;         bf16x8 q[3][2]; f32x4 o[3][4]; float m[3], l[3], snk[3];
; #pragma unroll
;         for (int g = 0; g < 3; ++g) { const bf16_t* qp = proj + (rowb + posq) * NIN + C_QC + (3 * kvh + g) * 64 + quad * 8; q[g][0] = *(const bf16x8*)qp; q[g][1] = *(const bf16x8*)(qp + 32);
;             o[g][0] = z4; o[g][1] = z4; o[g][2] = z4; o[g][3] = z4; snk[g] = ((const float*)(F.ws + WS_PAR))[32 + layer * 12 + 3 * kvh + g]; m[g] = snk[g]; l[g] = 0.f; }
;         if (P0 >= 128 && P0 + 160 <= T.S) mixer_c_item<false>(kp, vp, T.S, P0, lut, vimg, lane, q, o, m, l);
.LBB0_603:
	s_and_b64 vcc, exec, s[0:1]
	s_cbranch_vccz .LBB0_598
	s_mul_i32 s0, s46, 0x303
	v_add_u32_e32 v0, s0, v198
	v_ashrrev_i32_e32 v1, 31, v0
	v_lshl_add_u64 v[0:1], v[0:1], 2, s[92:93]
	s_mov_b64 s[0:1], 0
	v_or_b32_e32 v2, 0xffffffc0, v198
	v_mov_b32_e32 v3, v149
	global_load_dword v209, v[0:1], off
	global_load_dword v210, v[0:1], off offset:256
	global_load_dword v211, v[0:1], off offset:512
	global_load_dword v212, v[0:1], off offset:768
	global_load_dword v213, v[0:1], off offset:1024
	global_load_dword v214, v[0:1], off offset:1280
	global_load_dword v215, v[0:1], off offset:1536
	global_load_dword v216, v[0:1], off offset:1792
	global_load_dword v217, v[0:1], off offset:2048
	global_load_dword v218, v[0:1], off offset:2304
	global_load_dword v219, v[0:1], off offset:2560
	global_load_dword v220, v[0:1], off offset:2816
	v_cmp_gt_u32_e32 vcc, 3, v198
	s_and_saveexec_b64 s[0:1], vcc
	global_load_dword v221, v[0:1], off offset:3072
	s_waitcnt vmcnt(0)
	ds_write_b32 v3, v221 offset:3072
	s_mov_b64 exec, s[0:1]
	ds_write_b32 v3, v209
	ds_write_b32 v3, v210 offset:256
	ds_write_b32 v3, v211 offset:512
	ds_write_b32 v3, v212 offset:768
	ds_write_b32 v3, v213 offset:1024
	ds_write_b32 v3, v214 offset:1280
	ds_write_b32 v3, v215 offset:1536
	ds_write_b32 v3, v216 offset:1792
	ds_write_b32 v3, v217 offset:2048
	ds_write_b32 v3, v218 offset:2304
	ds_write_b32 v3, v219 offset:2560
	ds_write_b32 v3, v220 offset:2816
	s_abs_i32 s1, s47
	s_mul_hi_u32 s2, s1, s36
	s_mul_i32 s3, s2, s28
	s_sub_i32 s1, s1, s3
	s_ashr_i32 s0, s47, 31
	s_add_i32 s3, s2, 1
	s_sub_i32 s4, s1, s28
	s_cmp_ge_u32 s1, s28
	s_cselect_b32 s2, s3, s2
	s_cselect_b32 s1, s4, s1
	s_add_i32 s3, s2, 1
	s_cmp_ge_u32 s1, s28
	s_cselect_b32 s1, s3, s2
	s_xor_b32 s1, s1, s0
	s_sub_i32 s0, s1, s0
	s_mul_i32 s1, s0, s28
	s_sub_i32 s4, s47, s1
	s_ashr_i32 s1, s0, 31
	s_lshl_b64 s[0:1], s[0:1], s84
	s_mul_i32 s2, s1, 0x2800
	s_mul_hi_u32 s3, s0, 0x2800
	s_add_i32 s3, s3, s2
	s_mul_i32 s2, s0, 0x2800
	s_add_u32 s5, s88, s2
	s_addc_u32 s6, s89, s3
	s_lshl_b32 s2, s46, 6
	s_ashr_i32 s3, s2, 31
	s_lshl_b32 s52, s4, 4
	v_or_b32_e32 v0, s52, v199
	s_lshl_b64 s[2:3], s[2:3], 1
	s_add_u32 s2, s5, s2
	v_ashrrev_i32_e32 v1, 31, v0
	s_addc_u32 s3, s6, s3
	v_lshl_add_u64 v[140:141], s[0:1], 0, v[0:1]
	v_mov_b64_e32 v[0:1], s[88:89]
	s_add_u32 s44, s2, 0x2400
	v_mad_u64_u32 v[0:1], s[0:1], v140, s97, v[0:1]
	s_addc_u32 s45, s3, 0
	v_mad_i32_i24 v1, v141, s97, v1
	v_mov_b32_e32 v167, v157
	s_add_u32 s24, s2, 0x2600
	s_mul_i32 s2, s46, 3
	v_lshl_add_u64 v[0:1], v[0:1], 0, v[166:167]
	s_mov_b64 s[0:1], 0x1e00
	s_addc_u32 s25, s3, 0
	v_lshl_add_u64 v[0:1], v[0:1], 0, s[0:1]
	s_add_i32 s0, s31, s2
	s_mul_i32 s38, s46, 0xc0
	s_ashr_i32 s1, s0, 31
	s_ashr_i32 s39, s38, 31
	s_lshl_b64 s[0:1], s[0:1], 2
	s_add_u32 s0, s41, s0
	s_addc_u32 s1, s42, s1
	s_add_i32 s90, s38, 64
	s_add_i32 s66, s38, 0x80
	s_waitcnt lgkmcnt(0)
	v_lshl_add_u64 v[2:3], s[38:39], 1, v[0:1]
	s_ashr_i32 s91, s90, 31
	s_ashr_i32 s67, s66, 31
	global_load_dwordx4 v[16:19], v[2:3], off
	global_load_dwordx4 v[20:23], v[2:3], off offset:64
	global_load_dwordx3 v[136:138], v157, s[0:1]
	v_lshl_add_u64 v[2:3], s[90:91], 1, v[0:1]
	v_lshl_add_u64 v[0:1], s[66:67], 1, v[0:1]
	global_load_dwordx4 v[8:11], v[2:3], off
	global_load_dwordx4 v[12:15], v[2:3], off offset:64
	global_load_dwordx4 v[4:7], v[0:1], off
	s_nop 0
	global_load_dwordx4 v[0:3], v[0:1], off offset:64
	s_cmp_lt_i32 s4, 8
	s_cselect_b64 s[0:1], -1, 0
	s_cmp_gt_i32 s52, s35
	s_cselect_b64 s[2:3], -1, 0
	s_or_b64 s[2:3], s[0:1], s[2:3]
	s_mov_b64 s[0:1], -1
	s_andn2_b64 vcc, exec, s[2:3]
	v_lshlrev_b32_e32 v142, 1, v201
	s_waitcnt vmcnt(4)
	v_mov_b32_e32 v147, v137
	v_mov_b32_e32 v146, v138
	s_cbranch_vccz .LBB0_628
	s_mov_b32 s0, s52
	s_movk_i32 s1, 0xff80
	s_add_i32 s2, s0, s1
	v_lshl_add_u64 v[144:145], s[44:45], 0, v[156:157]
	v_add_u32_e32 v26, s2, v199
	v_mad_i64_i32 v[24:25], s[0:1], v26, s97, v[144:145]
	v_mov_b32_e32 v143, v157
	global_load_dwordx4 v[36:39], v[24:25], off
	global_load_dwordx4 v[32:35], v[24:25], off offset:64
	v_add_u32_e32 v24, 16, v26
	v_lshl_add_u64 v[146:147], s[24:25], 0, v[142:143]
	v_add_u32_e32 v44, s2, v200
	v_mad_i64_i32 v[24:25], s[0:1], v24, s97, v[144:145]
	v_mad_i64_i32 v[40:41], s[0:1], v44, s97, v[146:147]
	v_add_u32_e32 v42, 8, v44
	global_load_dwordx4 v[28:31], v[24:25], off
	s_nop 0
	global_load_dwordx4 v[24:27], v[24:25], off offset:64
	v_mad_i64_i32 v[42:43], s[0:1], v42, s97, v[146:147]
	global_load_dwordx4 v[104:107], v[40:41], off
	global_load_dwordx4 v[108:111], v[42:43], off
	v_add_u32_e32 v40, 16, v44
	v_mad_i64_i32 v[40:41], s[0:1], v40, s97, v[146:147]
	v_add_u32_e32 v42, 24, v44
	v_mad_i64_i32 v[42:43], s[0:1], v42, s97, v[146:147]
	global_load_dwordx4 v[112:115], v[40:41], off
	global_load_dwordx4 v[116:119], v[42:43], off
	s_not_b32 s0, s52
	v_readlane_b32 s1, v255, 21
	s_add_i32 s0, s1, s0
	v_min_i32_e32 v40, s0, v148
	v_mov_b32_e32 v42, v157
	v_mov_b32_e32 v43, v157
	v_sub_u32_e32 v153, v40, v139
	v_mov_b32_e32 v40, v157
	v_mov_b32_e32 v41, v157
	v_mov_b64_e32 v[46:47], v[42:43]
	v_mov_b64_e32 v[50:51], v[42:43]
	v_mov_b64_e32 v[62:63], v[42:43]
	v_mov_b64_e32 v[86:87], v[42:43]
	v_mov_b64_e32 v[82:83], v[42:43]
	v_mov_b64_e32 v[74:75], v[42:43]
	v_mov_b64_e32 v[78:79], v[42:43]
	v_mov_b64_e32 v[98:99], v[42:43]
	v_mov_b64_e32 v[90:91], v[42:43]
	v_mov_b64_e32 v[94:95], v[42:43]
	v_mov_b64_e32 v[102:103], v[42:43]
	v_mov_b32_e32 v152, 0
	s_mov_b32 s0, -2
	s_movk_i32 s1, 0xffc0
	v_mov_b64_e32 v[44:45], v[40:41]
	v_mov_b64_e32 v[48:49], v[40:41]
	v_mov_b64_e32 v[60:61], v[40:41]
	v_mov_b32_e32 v151, v138
	v_mov_b64_e32 v[84:85], v[40:41]
	v_mov_b64_e32 v[80:81], v[40:41]
	v_mov_b64_e32 v[72:73], v[40:41]
	v_mov_b64_e32 v[76:77], v[40:41]
	v_mov_b32_e32 v154, 0
	v_mov_b32_e32 v143, v137
	v_mov_b64_e32 v[96:97], v[40:41]
	v_mov_b64_e32 v[88:89], v[40:41]
	v_mov_b64_e32 v[92:93], v[40:41]
	v_mov_b64_e32 v[100:101], v[40:41]
	v_mov_b32_e32 v161, 0
	v_mov_b32_e32 v150, v136
	s_branch .LBB0_609
